# grid barrier P3->P4 replaced by per-wave arrivals (scan / kv2 counted separately, XCC last arriver writes back) + local waits before ret_out and knorm; guarded by placement flag
# baseline (speedup 1.0000x reference)
.LBB0_538:
	s_cmp_lg_u32 s98, 0
	s_cbranch_scc0 .Lp3_noarr
	s_waitcnt vmcnt(0)
	v_readlane_b32 s99, v254, 25
	v_readlane_b32 s100, v254, 24
	s_nop 3
	s_lshl_b32 s100, s100, 7
	s_cmp_ge_u32 s99, 4
	s_cselect_b32 s99, 0x900, 0
	s_add_i32 s99, s99, 0xfa0e100
	s_add_i32 s100, s100, s99
	v_mov_b32_e32 v0, s100
	s_add_i32 s99, s99, 0x800
	v_mov_b32_e32 v4, s99
	v_mov_b32_e32 v1, 1
	s_mov_b64 s[100:101], exec
	s_mov_b64 exec, 1
	v_mov_b32_e32 v3, 0x21000
	ds_read_b32 v3, v3
	global_atomic_add v2, v0, v1, s[74:75] sc0
	s_waitcnt vmcnt(0) lgkmcnt(0)
	v_add_u32_e32 v2, 1, v2
	v_lshlrev_b32_e32 v3, 2, v3
	v_cmp_eq_u32_e32 vcc, v2, v3
	s_cbranch_vccz .Lp3_arrd
	buffer_wbl2 sc1
	s_waitcnt vmcnt(0)
	global_atomic_add v4, v1, s[74:75]

.Lp3_noarr:
	s_waitcnt vmcnt(0)
	s_and_b64 vcc, exec, s[66:67]
	s_barrier
	s_cbranch_vccnz .LBB0_592
	s_cmp_lg_u32 s98, 0
	s_cbranch_scc0 .Lb4_orig
	s_mov_b64 s[100:101], exec
	s_mov_b64 exec, 1
	v_mov_b32_e32 v0, 0x21004
	ds_read_b32 v1, v0
	v_mov_b32_e32 v0, 0xfa0e900
	s_mov_b32 s99, 0
	s_waitcnt lgkmcnt(0)

.Lb4_orig:
	v_mbcnt_lo_u32_b32 v0, -1, 0
	v_mbcnt_hi_u32_b32 v0, -1, v0
	s_nop 0
	v_cmp_eq_u32_e32 vcc, 0, v0
	s_and_saveexec_b64 s[0:1], vcc
	s_cbranch_execz .LBB0_591
	s_add_i32 s2, 0, 0x21000
	v_mov_b32_e32 v0, s2
	s_waitcnt vmcnt(0) expcnt(0) lgkmcnt(0)
	ds_read_b32 v2, v0
	s_add_i32 s2, 0, 0x21004
	v_mov_b32_e32 v0, s2
	ds_read_b32 v0, v0
	s_waitcnt lgkmcnt(1)
	v_cmp_ne_u32_e32 vcc, 0, v2
	s_cbranch_vccnz .LBB0_555
	s_add_u32 s4, s74, 0xfa00200
	s_addc_u32 s5, s75, 0
	s_add_u32 s6, s74, 0xfa00400
	s_addc_u32 s7, s75, 0
	s_add_u32 s10, s74, 0xfa00500
	s_addc_u32 s11, s75, 0
	s_add_u32 s12, s74, 0xfa00600
	s_addc_u32 s13, s75, 0
	s_add_u32 s14, s74, 0xfa00700
	s_addc_u32 s15, s75, 0
	s_add_u32 s16, s74, 0xfa00800
	s_addc_u32 s17, s75, 0
	s_add_u32 s18, s74, 0xfa00900
	s_addc_u32 s19, s75, 0
	s_add_u32 s20, s74, 0xfa00a00
	s_addc_u32 s21, s75, 0
	s_add_u32 s22, s74, 0xfa00b00
	s_addc_u32 s23, s75, 0
	s_add_u32 s24, s74, 0xfa00c00
	s_addc_u32 s25, s75, 0
	s_add_u32 s26, s74, 0xfa00d00
	s_addc_u32 s27, s75, 0
	s_add_u32 s28, s74, 0xfa00e00
	s_addc_u32 s29, s75, 0
	s_add_u32 s30, s74, 0xfa00f00
	s_addc_u32 s31, s75, 0
	s_add_u32 s34, s74, 0xfa01000
	s_addc_u32 s35, s75, 0
	s_add_u32 s36, s74, 0xfa01100
	s_addc_u32 s37, s75, 0
	s_add_u32 s38, s74, 0xfa01200
	v_readlane_b32 s2, v254, 4
	s_addc_u32 s39, s75, 0
	s_mul_i32 s2, s79, s2
	s_add_u32 s46, s74, 0xfa01300
	s_mul_i32 s2, s2, s78
	s_addc_u32 s47, s75, 0
	s_mov_b32 s3, 1
	v_mov_b32_e32 v16, 0
	s_branch .LBB0_543

.LBB0_598:
	s_cmp_lg_u32 s98, 0
	s_cbranch_scc0 .Lkn_nowait
	v_readlane_b32 s99, v254, 25
	s_nop 3
	s_cmp_lg_u32 s99, 0
	s_cbranch_scc1 .Lkn_nowait
	s_mov_b64 s[100:101], exec
	s_mov_b64 exec, 1
	v_mov_b32_e32 v0, 0x21004
	ds_read_b32 v1, v0
	v_mov_b32_e32 v0, 0xfa0f200
	s_mov_b32 s99, 0
	s_waitcnt lgkmcnt(0)

.Lkn_done:
	buffer_inv sc1
	s_waitcnt vmcnt(0)
	s_mov_b64 exec, s[100:101]
.Lkn_nowait:
	v_readlane_b32 s0, v254, 26
	s_cmpk_gt_i32 s0, 0x7ff
	s_barrier
	v_readlane_b32 s1, v254, 27
	v_mbcnt_lo_u32_b32 v0, -1, 0
	v_mbcnt_hi_u32_b32 v0, -1, v0
	s_cbranch_scc1 .LBB0_601
	v_lshlrev_b32_e32 v0, 2, v0
	v_readlane_b32 s8, v254, 28
	v_readlane_b32 s1, v254, 25
	v_ashrrev_i32_e32 v1, 31, v0
	v_readlane_b32 s9, v254, 29
	v_readlane_b32 s10, v254, 30
	v_readlane_b32 s11, v254, 31
	v_readlane_b32 s22, v254, 42
	v_readlane_b32 s23, v254, 43
	s_lshl_b32 s0, s70, 11
	s_lshl_b32 s1, s1, 8
	v_readlane_b32 s8, v254, 26
	v_lshl_add_u64 v[2:3], v[0:1], 2, s[22:23]
	s_add_i32 s0, s0, s1
	s_lshl_b32 s1, s78, 11
	v_mov_b32_e32 v4, 0x358637bd
	s_mov_b32 s2, 0x800000
	v_readlane_b32 s10, v254, 57
	v_readlane_b32 s12, v254, 32
	v_readlane_b32 s13, v254, 33
	v_readlane_b32 s14, v254, 34
	v_readlane_b32 s15, v254, 35
	v_readlane_b32 s16, v254, 36
	v_readlane_b32 s17, v254, 37
	v_readlane_b32 s18, v254, 38
	v_readlane_b32 s19, v254, 39
	v_readlane_b32 s20, v254, 40
	v_readlane_b32 s21, v254, 41
	v_readlane_b32 s9, v254, 27
	v_readlane_b32 s11, v254, 58
